# forgetting mixer: cross-wave bound ds_read hoisted into the PV block (overlaps MFMAs), skip paths issue it before branching; on top of v_all4
# baseline (speedup 1.0000x reference)
.LBB0_345:
	v_mov_b32_e32 v123, v121
	v_mov_b32_e32 v0, s23
	ds_read_b32 v122, v0
	s_branch .LBB0_354

; #define LAS __attribute__((address_space(3)))
; #define ATT_SB() __builtin_amdgcn_sched_barrier(0)
; template <int MODE>
; __device__ __forceinline__ void att_tile(LAS unsigned char* lds, int buf, int kv0, int wq0, int r32, int hi, int mapi, const bf16x8 (&qr)[4], f32x16 (&O)[AttCfg<MODE>::NC], float& mrun, float& lsum, LAS float* wsf, bool fixed = false  ) {
;     ...
;     float ps = 0.f;
; #pragma unroll
;     for (int r = 0; r < 16; ++r) { p0[r] = __builtin_amdgcn_exp2f(p0[r] - msafe); p1[r] = __builtin_amdgcn_exp2f(p1[r] - msafe); ps += p0[r] + p1[r]; }
;     lsum = lsum * alpha + ps;
;     if (!fixed) {
;     if (__any(alpha != 1.0f)) {
;         if (hi == 0) wsf[r32] = alpha;
;         asm volatile("s_waitcnt lgkmcnt(0)" ::: "memory");
; #pragma unroll
;         for (int i = 0; i < 4; ++i) { const f32x4 av = *(const LAS f32x4*)(wsf + 8 * i + 4 * hi);
; #pragma unroll
;             for (int c = 0; c < NC; ++c)
; #pragma unroll
;                 for (int k = 0; k < 4; ++k) O[c][4 * i + k] *= av[k]; }
;         asm volatile("s_waitcnt lgkmcnt(0)" ::: "memory");
;     }
;     }
;     bf16x8 pa[4];
;     { u32x4 w;
;       w.x = pk2(p0[0], p0[1]); w.y = pk2(p0[2], p0[3]); w.z = pk2(p0[4], p0[5]); w.w = pk2(p0[6], p0[7]); pa[0] = __builtin_bit_cast(bf16x8, w);
;       w.x = pk2(p0[8], p0[9]); w.y = pk2(p0[10], p0[11]); w.z = pk2(p0[12], p0[13]); w.w = pk2(p0[14], p0[15]); pa[1] = __builtin_bit_cast(bf16x8, w);
;       w.x = pk2(p1[0], p1[1]); w.y = pk2(p1[2], p1[3]); w.z = pk2(p1[4], p1[5]); w.w = pk2(p1[6], p1[7]); pa[2] = __builtin_bit_cast(bf16x8, w);
;       w.x = pk2(p1[8], p1[9]); w.y = pk2(p1[10], p1[11]); w.z = pk2(p1[12], p1[13]); w.w = pk2(p1[14], p1[15]); pa[3] = __builtin_bit_cast(bf16x8, w); }
;     ATT_SB();
;     u32x4 vg[2 * NC];
; #pragma unroll
;     for (int j = 0; j < 2; ++j)
; #pragma unroll
;         for (int c = 0; c < NC; ++c) { const u32x2 lo = *(const LAS u32x2*)(vb + c * 32 * C::VSTR + (j + 2) * 32), hh = *(const LAS u32x2*)(vb + c * 32 * C::VSTR + (j + 2) * 32 + 16); vg[j * NC + c] = (u32x4){lo.x, lo.y, hh.x, hh.y}; }
;     ATT_SB();
; #pragma unroll
;     for (int j = 0; j < 2; ++j)
; #pragma unroll
;         for (int c = 0; c < NC; ++c) O[c] = __builtin_amdgcn_mfma_f32_32x32x16_bf16(pa[j], __builtin_bit_cast(bf16x8, vf[j * NC + c]), O[c], 0, 0, 0);
;     ATT_SB();
; #pragma unroll
;     for (int j = 0; j < 2; ++j)
; #pragma unroll
.LBB0_353:
	s_nop 0
	v_sub_f32_e32 v50, v50, v152
	s_nop 0
	v_sub_f32_e32 v34, v34, v152
	v_exp_f32_e32 v50, v50
	v_exp_f32_e32 v121, v34
	v_sub_f32_e32 v34, v51, v152
	v_sub_f32_e32 v35, v35, v152
	v_exp_f32_e32 v34, v34
	v_exp_f32_e32 v51, v35
	v_sub_f32_e32 v52, v52, v152
	v_sub_f32_e32 v36, v36, v152
	v_add_f32_e32 v35, v121, v50
	v_exp_f32_e32 v52, v52
	v_exp_f32_e32 v154, v36
	v_sub_f32_e32 v36, v53, v152
	v_sub_f32_e32 v37, v37, v152
	v_add_f32_e32 v35, 0, v35
	v_add_f32_e32 v153, v51, v34
	v_exp_f32_e32 v36, v36
	v_exp_f32_e32 v53, v37
	v_sub_f32_e32 v54, v54, v152
	v_sub_f32_e32 v38, v38, v152
	v_add_f32_e32 v35, v153, v35
	v_exp_f32_e32 v54, v54
	v_exp_f32_e32 v153, v38
	v_sub_f32_e32 v38, v55, v152
	v_sub_f32_e32 v39, v39, v152
	v_exp_f32_e32 v38, v38
	v_exp_f32_e32 v55, v39
	v_sub_f32_e32 v39, v56, v152
	v_sub_f32_e32 v40, v40, v152
	v_add_f32_e32 v37, v154, v52
	v_exp_f32_e32 v39, v39
	v_exp_f32_e32 v56, v40
	v_sub_f32_e32 v40, v57, v152
	v_sub_f32_e32 v41, v41, v152
	v_add_f32_e32 v35, v37, v35
	v_add_f32_e32 v37, v53, v36
	v_exp_f32_e32 v40, v40
	v_exp_f32_e32 v57, v41
	v_sub_f32_e32 v41, v58, v152
	v_sub_f32_e32 v42, v42, v152
	v_add_f32_e32 v35, v37, v35
	v_add_f32_e32 v37, v153, v54
	v_exp_f32_e32 v41, v41
	v_exp_f32_e32 v58, v42
	v_sub_f32_e32 v42, v59, v152
	v_sub_f32_e32 v43, v43, v152
	v_add_f32_e32 v35, v37, v35
	v_add_f32_e32 v37, v55, v38
	v_exp_f32_e32 v42, v42
	v_exp_f32_e32 v59, v43
	v_sub_f32_e32 v43, v60, v152
	v_sub_f32_e32 v44, v44, v152
	v_add_f32_e32 v35, v37, v35
	v_add_f32_e32 v37, v56, v39
	v_exp_f32_e32 v43, v43
	v_exp_f32_e32 v60, v44
	v_sub_f32_e32 v44, v61, v152
	v_sub_f32_e32 v45, v45, v152
	v_add_f32_e32 v35, v37, v35
	v_add_f32_e32 v37, v57, v40
	v_exp_f32_e32 v44, v44
	v_exp_f32_e32 v61, v45
	v_sub_f32_e32 v45, v62, v152
	v_sub_f32_e32 v46, v46, v152
	v_add_f32_e32 v35, v37, v35
	v_add_f32_e32 v37, v58, v41
	v_exp_f32_e32 v45, v45
	v_exp_f32_e32 v62, v46
	v_sub_f32_e32 v46, v63, v152
	v_sub_f32_e32 v47, v47, v152
	v_add_f32_e32 v35, v37, v35
	v_add_f32_e32 v37, v59, v42
	v_exp_f32_e32 v46, v46
	v_exp_f32_e32 v63, v47
	v_sub_f32_e32 v47, v64, v152
	v_sub_f32_e32 v48, v48, v152
	v_add_f32_e32 v35, v37, v35
	v_add_f32_e32 v37, v60, v43
	v_exp_f32_e32 v47, v47
	v_exp_f32_e32 v64, v48
	v_sub_f32_e32 v48, v65, v152
	v_sub_f32_e32 v49, v49, v152
	v_add_f32_e32 v35, v37, v35
	v_add_f32_e32 v37, v61, v44
	v_exp_f32_e32 v48, v48
	v_exp_f32_e32 v49, v49
	v_add_f32_e32 v35, v37, v35
	v_add_f32_e32 v37, v62, v45
	v_add_f32_e32 v35, v37, v35
	v_add_f32_e32 v37, v63, v46
	v_add_f32_e32 v35, v37, v35
	v_add_f32_e32 v37, v64, v47
	v_add_f32_e32 v35, v37, v35
	v_add_f32_e32 v37, v49, v48
	v_add_f32_e32 v152, v37, v35
	v_fmac_f32_e32 v152, v151, v122
	v_mov_b32_e32 v122, s23
	ds_read_b32 v122, v122
	v_cvt_pk_bf16_f32 v34, v50, v34
	v_cvt_pk_bf16_f32 v35, v52, v36
	v_cvt_pk_bf16_f32 v36, v54, v38
	v_cvt_pk_bf16_f32 v37, v39, v40
	v_cvt_pk_bf16_f32 v38, v41, v42
	v_cvt_pk_bf16_f32 v39, v43, v44
	v_cvt_pk_bf16_f32 v40, v45, v46
	v_cvt_pk_bf16_f32 v41, v47, v48
	v_cvt_pk_bf16_f32 v42, v121, v51
	v_cvt_pk_bf16_f32 v43, v154, v53
	v_cvt_pk_bf16_f32 v44, v153, v55
	v_cvt_pk_bf16_f32 v45, v56, v57
	v_cvt_pk_bf16_f32 v46, v58, v59
	v_cvt_pk_bf16_f32 v47, v60, v61
	v_cvt_pk_bf16_f32 v48, v62, v63
	v_cvt_pk_bf16_f32 v49, v64, v49
	ds_read2_b64 v[50:53], v120 offset0:8 offset1:10
	ds_read2_b64 v[54:57], v120 offset0:12 offset1:14
	ds_read2_b64 v[58:61], v0 offset0:40 offset1:42
	ds_read2_b64 v[62:65], v0 offset0:44 offset1:46
	s_waitcnt lgkmcnt(7)
	v_mfma_f32_32x32x16_bf16 v[2:17], v[34:37], v[110:113], v[2:17]
	s_waitcnt lgkmcnt(5)
	v_mfma_f32_32x32x16_bf16 v[18:33], v[34:37], v[106:109], v[18:33]
	v_mfma_f32_32x32x16_bf16 v[2:17], v[38:41], v[98:101], v[2:17]
	s_waitcnt lgkmcnt(4)
	v_mfma_f32_32x32x16_bf16 v[18:33], v[38:41], v[102:105], v[18:33]
	s_waitcnt lgkmcnt(3)
	v_mfma_f32_32x32x16_bf16 v[2:17], v[42:45], v[50:53], v[2:17]
	s_waitcnt lgkmcnt(1)
	v_mfma_f32_32x32x16_bf16 v[18:33], v[42:45], v[58:61], v[18:33]
	v_mfma_f32_32x32x16_bf16 v[2:17], v[46:49], v[54:57], v[2:17]
	s_waitcnt lgkmcnt(0)
	v_mfma_f32_32x32x16_bf16 v[18:33], v[46:49], v[62:65], v[18:33]
	v_mov_b32_e32 v151, v152
.LBB0_354:
	s_waitcnt lgkmcnt(0)
	v_pk_add_f32 v[34:35], v[198:199], v[122:123]
	s_nop 0
	v_cmp_gt_f32_e32 vcc, v34, v35
	s_cmp_lg_u64 vcc, 0
	s_cselect_b64 s[14:15], -1, 0
	s_and_saveexec_b64 s[16:17], s[40:41]
	v_cndmask_b32_e64 v0, 0, 1, s[14:15]
	v_mov_b32_e32 v34, s29
	ds_write_b32 v34, v0
	s_or_b64 exec, exec, s[16:17]
	s_add_i32 s72, s68, -1
	s_cmp_lt_u32 s72, s85
	s_cselect_b64 s[18:19], -1, 0
	s_cmp_ge_u32 s72, s85
	s_cbranch_scc1 .LBB0_359
	v_add_u32_e32 v0, 0xaa00, v135
	s_and_b64 vcc, exec, s[36:37]
	s_cmp_lg_u64 s[10:11], 0
	s_cbranch_scc1 .Lfv_a_own
	s_waitcnt vmcnt(1)
	ds_write_b128 v134, v[90:93] offset:9216
	s_waitcnt vmcnt(0)
	s_branch .Lfv_a_join

.LBB0_371:
	v_mov_b32_e32 v121, v123
	v_mov_b32_e32 v0, s60
	ds_read_b32 v120, v0
	s_branch .LBB0_380

; #define LAS __attribute__((address_space(3)))
; #define ATT_SB() __builtin_amdgcn_sched_barrier(0)
; template <int MODE>
; __device__ __forceinline__ void att_tile(LAS unsigned char* lds, int buf, int kv0, int wq0, int r32, int hi, int mapi, const bf16x8 (&qr)[4], f32x16 (&O)[AttCfg<MODE>::NC], float& mrun, float& lsum, LAS float* wsf, bool fixed = false  ) {
;     ...
;     float ps = 0.f;
; #pragma unroll
;     for (int r = 0; r < 16; ++r) { p0[r] = __builtin_amdgcn_exp2f(p0[r] - msafe); p1[r] = __builtin_amdgcn_exp2f(p1[r] - msafe); ps += p0[r] + p1[r]; }
;     lsum = lsum * alpha + ps;
;     if (!fixed) {
;     if (__any(alpha != 1.0f)) {
;         if (hi == 0) wsf[r32] = alpha;
;         asm volatile("s_waitcnt lgkmcnt(0)" ::: "memory");
; #pragma unroll
;         for (int i = 0; i < 4; ++i) { const f32x4 av = *(const LAS f32x4*)(wsf + 8 * i + 4 * hi);
; #pragma unroll
;             for (int c = 0; c < NC; ++c)
; #pragma unroll
;                 for (int k = 0; k < 4; ++k) O[c][4 * i + k] *= av[k]; }
;         asm volatile("s_waitcnt lgkmcnt(0)" ::: "memory");
;     }
;     }
;     bf16x8 pa[4];
;     { u32x4 w;
;       w.x = pk2(p0[0], p0[1]); w.y = pk2(p0[2], p0[3]); w.z = pk2(p0[4], p0[5]); w.w = pk2(p0[6], p0[7]); pa[0] = __builtin_bit_cast(bf16x8, w);
;       w.x = pk2(p0[8], p0[9]); w.y = pk2(p0[10], p0[11]); w.z = pk2(p0[12], p0[13]); w.w = pk2(p0[14], p0[15]); pa[1] = __builtin_bit_cast(bf16x8, w);
;       w.x = pk2(p1[0], p1[1]); w.y = pk2(p1[2], p1[3]); w.z = pk2(p1[4], p1[5]); w.w = pk2(p1[6], p1[7]); pa[2] = __builtin_bit_cast(bf16x8, w);
;       w.x = pk2(p1[8], p1[9]); w.y = pk2(p1[10], p1[11]); w.z = pk2(p1[12], p1[13]); w.w = pk2(p1[14], p1[15]); pa[3] = __builtin_bit_cast(bf16x8, w); }
;     ATT_SB();
;     u32x4 vg[2 * NC];
; #pragma unroll
;     for (int j = 0; j < 2; ++j)
; #pragma unroll
;         for (int c = 0; c < NC; ++c) { const u32x2 lo = *(const LAS u32x2*)(vb + c * 32 * C::VSTR + (j + 2) * 32), hh = *(const LAS u32x2*)(vb + c * 32 * C::VSTR + (j + 2) * 32 + 16); vg[j * NC + c] = (u32x4){lo.x, lo.y, hh.x, hh.y}; }
;     ATT_SB();
; #pragma unroll
;     for (int j = 0; j < 2; ++j)
; #pragma unroll
;         for (int c = 0; c < NC; ++c) O[c] = __builtin_amdgcn_mfma_f32_32x32x16_bf16(pa[j], __builtin_bit_cast(bf16x8, vf[j * NC + c]), O[c], 0, 0, 0);
;     ATT_SB();
; #pragma unroll
;     for (int j = 0; j < 2; ++j)
; #pragma unroll
.LBB0_379:
	v_sub_f32_e32 v50, v50, v152
	s_nop 0
	v_sub_f32_e32 v34, v34, v152
	v_exp_f32_e32 v50, v50
	v_exp_f32_e32 v123, v34
	v_sub_f32_e32 v34, v51, v152
	v_sub_f32_e32 v35, v35, v152
	v_exp_f32_e32 v34, v34
	v_exp_f32_e32 v51, v35
	v_sub_f32_e32 v52, v52, v152
	v_sub_f32_e32 v36, v36, v152
	v_add_f32_e32 v35, v123, v50
	v_exp_f32_e32 v52, v52
	v_exp_f32_e32 v154, v36
	v_sub_f32_e32 v36, v53, v152
	v_sub_f32_e32 v37, v37, v152
	v_add_f32_e32 v35, 0, v35
	v_add_f32_e32 v153, v51, v34
	v_exp_f32_e32 v36, v36
	v_exp_f32_e32 v53, v37
	v_sub_f32_e32 v54, v54, v152
	v_sub_f32_e32 v38, v38, v152
	v_add_f32_e32 v35, v153, v35
	v_exp_f32_e32 v54, v54
	v_exp_f32_e32 v153, v38
	v_sub_f32_e32 v38, v55, v152
	v_sub_f32_e32 v39, v39, v152
	v_exp_f32_e32 v38, v38
	v_exp_f32_e32 v55, v39
	v_sub_f32_e32 v39, v56, v152
	v_sub_f32_e32 v40, v40, v152
	v_add_f32_e32 v37, v154, v52
	v_exp_f32_e32 v39, v39
	v_exp_f32_e32 v56, v40
	v_sub_f32_e32 v40, v57, v152
	v_sub_f32_e32 v41, v41, v152
	v_add_f32_e32 v35, v37, v35
	v_add_f32_e32 v37, v53, v36
	v_exp_f32_e32 v40, v40
	v_exp_f32_e32 v57, v41
	v_sub_f32_e32 v41, v58, v152
	v_sub_f32_e32 v42, v42, v152
	v_add_f32_e32 v35, v37, v35
	v_add_f32_e32 v37, v153, v54
	v_exp_f32_e32 v41, v41
	v_exp_f32_e32 v58, v42
	v_sub_f32_e32 v42, v59, v152
	v_sub_f32_e32 v43, v43, v152
	v_add_f32_e32 v35, v37, v35
	v_add_f32_e32 v37, v55, v38
	v_exp_f32_e32 v42, v42
	v_exp_f32_e32 v59, v43
	v_sub_f32_e32 v43, v60, v152
	v_sub_f32_e32 v44, v44, v152
	v_add_f32_e32 v35, v37, v35
	v_add_f32_e32 v37, v56, v39
	v_exp_f32_e32 v43, v43
	v_exp_f32_e32 v60, v44
	v_sub_f32_e32 v44, v61, v152
	v_sub_f32_e32 v45, v45, v152
	v_add_f32_e32 v35, v37, v35
	v_add_f32_e32 v37, v57, v40
	v_exp_f32_e32 v44, v44
	v_exp_f32_e32 v61, v45
	v_sub_f32_e32 v45, v62, v152
	v_sub_f32_e32 v46, v46, v152
	v_add_f32_e32 v35, v37, v35
	v_add_f32_e32 v37, v58, v41
	v_exp_f32_e32 v45, v45
	v_exp_f32_e32 v62, v46
	v_sub_f32_e32 v46, v63, v152
	v_sub_f32_e32 v47, v47, v152
	v_add_f32_e32 v35, v37, v35
	v_add_f32_e32 v37, v59, v42
	v_exp_f32_e32 v46, v46
	v_exp_f32_e32 v63, v47
	v_sub_f32_e32 v47, v64, v152
	v_sub_f32_e32 v48, v48, v152
	v_add_f32_e32 v35, v37, v35
	v_add_f32_e32 v37, v60, v43
	v_exp_f32_e32 v47, v47
	v_exp_f32_e32 v64, v48
	v_sub_f32_e32 v48, v65, v152
	v_sub_f32_e32 v49, v49, v152
	v_add_f32_e32 v35, v37, v35
	v_add_f32_e32 v37, v61, v44
	v_exp_f32_e32 v48, v48
	v_exp_f32_e32 v49, v49
	v_add_f32_e32 v35, v37, v35
	v_add_f32_e32 v37, v62, v45
	v_add_f32_e32 v35, v37, v35
	v_add_f32_e32 v37, v63, v46
	v_add_f32_e32 v35, v37, v35
	v_add_f32_e32 v37, v64, v47
	v_add_f32_e32 v35, v37, v35
	v_add_f32_e32 v37, v49, v48
	v_add_f32_e32 v152, v37, v35
	v_fmac_f32_e32 v152, v151, v122
	v_cvt_pk_bf16_f32 v34, v50, v34
	v_cvt_pk_bf16_f32 v35, v52, v36
	v_cvt_pk_bf16_f32 v36, v54, v38
	v_cvt_pk_bf16_f32 v37, v39, v40
	v_cvt_pk_bf16_f32 v38, v41, v42
	v_cvt_pk_bf16_f32 v39, v43, v44
	v_cvt_pk_bf16_f32 v40, v45, v46
	v_cvt_pk_bf16_f32 v41, v47, v48
	v_cvt_pk_bf16_f32 v42, v123, v51
	v_cvt_pk_bf16_f32 v43, v154, v53
	v_cvt_pk_bf16_f32 v44, v153, v55
	v_cvt_pk_bf16_f32 v45, v56, v57
	v_cvt_pk_bf16_f32 v46, v58, v59
	v_cvt_pk_bf16_f32 v47, v60, v61
	v_cvt_pk_bf16_f32 v48, v62, v63
	v_cvt_pk_bf16_f32 v49, v64, v49
	ds_read2_b64 v[50:53], v120 offset0:72 offset1:74
	ds_read2_b64 v[54:57], v120 offset0:76 offset1:78
	ds_read2_b64 v[58:61], v0 offset0:104 offset1:106
	ds_read2_b64 v[62:65], v0 offset0:108 offset1:110
	v_mov_b32_e32 v0, s60
	ds_read_b32 v120, v0
	s_waitcnt lgkmcnt(8)
	v_mfma_f32_32x32x16_bf16 v[2:17], v[34:37], v[110:113], v[2:17]
	s_waitcnt lgkmcnt(6)
	v_mfma_f32_32x32x16_bf16 v[18:33], v[34:37], v[106:109], v[18:33]
	v_mfma_f32_32x32x16_bf16 v[2:17], v[38:41], v[98:101], v[2:17]
	s_waitcnt lgkmcnt(5)
	v_mfma_f32_32x32x16_bf16 v[18:33], v[38:41], v[102:105], v[18:33]
	s_waitcnt lgkmcnt(4)
	v_mfma_f32_32x32x16_bf16 v[2:17], v[42:45], v[50:53], v[2:17]
	s_waitcnt lgkmcnt(2)
	v_mfma_f32_32x32x16_bf16 v[18:33], v[42:45], v[58:61], v[18:33]
	v_mfma_f32_32x32x16_bf16 v[2:17], v[46:49], v[54:57], v[2:17]
	s_waitcnt lgkmcnt(1)
	v_mfma_f32_32x32x16_bf16 v[18:33], v[46:49], v[62:65], v[18:33]
	v_mov_b32_e32 v151, v152
.LBB0_380:
	s_waitcnt lgkmcnt(0)
	v_pk_add_f32 v[34:35], v[198:199], v[120:121]
	s_nop 0
	v_cmp_gt_f32_e32 vcc, v34, v35
	s_cmp_lg_u64 vcc, 0
	s_cselect_b64 s[14:15], -1, 0
	s_and_saveexec_b64 s[16:17], s[40:41]
	v_cndmask_b32_e64 v0, 0, 1, s[14:15]
	v_mov_b32_e32 v34, s29
	ds_write_b32 v34, v0 offset:32
	s_or_b64 exec, exec, s[16:17]
	s_andn2_b64 vcc, exec, s[10:11]
	s_cbranch_vccnz .LBB0_385
	s_and_b64 vcc, exec, s[36:37]
	s_cmp_lt_u32 s72, s85
	s_cbranch_scc1 .Lfv_b_own
	s_waitcnt vmcnt(1)
	ds_write_b128 v134, v[82:85]
	s_waitcnt vmcnt(0)
	s_branch .Lfv_b_join
